# remaining MFMA loop heads (attention streams, unit loops) aligned to 64 bytes
# baseline (speedup 1.0000x reference)
.LBB0_122:
	s_lshl_b32 s31, s30, 1
	s_bitcmp1_b32 s30, 0
	s_cselect_b32 s0, 0x9000, 0
	s_andn2_b32 s14, 1, s30
	s_mul_i32 s14, s14, 0x9000
	v_add_u32_e32 v0, s0, v73
	v_add_u32_e32 v74, s14, v3
	s_mov_b64 s[14:15], -1
	s_mov_b32 s38, 0
	s_branch .LBB0_124
	.p2align	6

.LBB0_128:
	s_waitcnt lgkmcnt(0)
	v_add_u32_e32 v32, s0, v0
	ds_read_b128 v[60:63], v32
	ds_read_b128 v[56:59], v32 offset:64
	ds_read_b128 v[52:55], v32 offset:2304
	ds_read_b128 v[48:51], v32 offset:2368
	ds_read_b128 v[44:47], v32 offset:4608
	ds_read_b128 v[40:43], v32 offset:4672
	ds_read_b128 v[36:39], v32 offset:6912
	ds_read_b128 v[32:35], v32 offset:6976
	s_lshl_b32 s36, s36, 6
	s_or_b32 s37, s36, 63
	s_max_u32 s37, s36, s37
	v_cmp_ge_u32_e32 vcc, s37, v174
	s_cbranch_vccz .LBB0_133
	v_add_u32_e32 v70, s36, v72
	v_or_b32_e32 v71, 1, v70
	v_cmp_lt_u32_e64 s[62:63], v71, v174
	v_or_b32_e32 v71, 2, v70
	v_cmp_lt_u32_e64 s[60:61], v71, v174
	v_or_b32_e32 v71, 3, v70
	v_cmp_lt_u32_e64 s[56:57], v71, v174
	v_add_u32_e32 v71, 16, v70
	v_cmp_lt_u32_e64 s[58:59], v71, v174
	v_add_u32_e32 v71, 17, v70
	v_cmp_lt_u32_e64 s[54:55], v71, v174
	v_add_u32_e32 v71, 18, v70
	v_cmp_lt_u32_e64 s[52:53], v71, v174
	v_add_u32_e32 v71, 19, v70
	s_waitcnt vmcnt(3) lgkmcnt(7)
	v_mfma_f32_16x16x32_bf16 v[76:79], v[60:63], v[4:7], v[20:23]
	v_cmp_lt_u32_e64 s[48:49], v71, v174
	v_add_u32_e32 v71, 32, v70
	v_cmp_lt_u32_e64 s[50:51], v71, v174
	s_waitcnt lgkmcnt(5)
	v_mfma_f32_16x16x32_bf16 v[80:83], v[52:55], v[4:7], v[20:23]
	v_add_u32_e32 v71, 33, v70
	v_cmp_lt_u32_e64 s[46:47], v71, v174
	v_add_u32_e32 v71, 34, v70
	s_waitcnt lgkmcnt(3)
	v_mfma_f32_16x16x32_bf16 v[84:87], v[44:47], v[4:7], v[20:23]
	v_cmp_lt_u32_e64 s[44:45], v71, v174
	v_add_u32_e32 v71, 35, v70
	v_cmp_lt_u32_e64 s[40:41], v71, v174
	s_waitcnt vmcnt(2)
	v_mfma_f32_16x16x32_bf16 v[76:79], v[56:59], v[8:11], v[76:79]
	v_add_u32_e32 v71, 48, v70
	v_cmp_lt_u32_e64 s[42:43], v71, v174
	v_add_u32_e32 v71, 49, v70
	s_waitcnt lgkmcnt(1)
	v_mfma_f32_16x16x32_bf16 v[88:91], v[36:39], v[4:7], v[20:23]
	v_cmp_lt_u32_e64 s[64:65], v70, v174
	v_cmp_lt_u32_e64 s[38:39], v71, v174
	v_add_u32_e32 v71, 50, v70
	v_mfma_f32_16x16x32_bf16 v[80:83], v[48:51], v[8:11], v[80:83]
	v_add_u32_e32 v70, 51, v70
	v_cmp_lt_u32_e64 s[36:37], v71, v174
	v_cmp_lt_u32_e32 vcc, v70, v174
	v_mfma_f32_16x16x32_bf16 v[84:87], v[40:43], v[8:11], v[84:87]
	v_exp_f32_e32 v70, v76
	v_exp_f32_e32 v71, v77
	v_exp_f32_e32 v75, v78
	s_waitcnt lgkmcnt(0)
	v_mfma_f32_16x16x32_bf16 v[88:91], v[32:35], v[8:11], v[88:91]
	v_exp_f32_e32 v76, v79
	v_exp_f32_e32 v77, v80
	v_exp_f32_e32 v78, v81
	v_exp_f32_e32 v79, v82
	v_exp_f32_e32 v80, v83
	v_exp_f32_e32 v81, v84
	v_exp_f32_e32 v82, v85
	v_exp_f32_e32 v83, v86
	v_exp_f32_e32 v84, v87
	v_cndmask_b32_e64 v70, 0, v70, s[64:65]
	v_cndmask_b32_e64 v71, 0, v71, s[62:63]
	v_cndmask_b32_e64 v75, 0, v75, s[60:61]
	v_cndmask_b32_e64 v76, 0, v76, s[56:57]
	v_exp_f32_e32 v85, v88
	v_exp_f32_e32 v86, v89
	v_exp_f32_e32 v87, v90
	v_exp_f32_e32 v88, v91
	v_cndmask_b32_e64 v77, 0, v77, s[58:59]
	v_cndmask_b32_e64 v78, 0, v78, s[54:55]
	v_cndmask_b32_e64 v79, 0, v79, s[52:53]
	v_cndmask_b32_e64 v80, 0, v80, s[48:49]
	v_add_f32_e32 v70, v70, v71
	v_add_f32_e32 v71, v75, v76
	v_add_f32_e32 v70, v70, v71
	v_add_f32_e32 v71, v77, v78
	v_add_f32_e32 v75, v79, v80
	v_cndmask_b32_e64 v81, 0, v81, s[50:51]
	v_cndmask_b32_e64 v82, 0, v82, s[46:47]
	v_cndmask_b32_e64 v83, 0, v83, s[44:45]
	v_cndmask_b32_e64 v84, 0, v84, s[40:41]
	v_add_f32_e32 v71, v71, v75
	v_cndmask_b32_e64 v85, 0, v85, s[42:43]
	v_cndmask_b32_e64 v86, 0, v86, s[38:39]
	v_cndmask_b32_e64 v87, 0, v87, s[36:37]
	v_cndmask_b32_e32 v88, 0, v88, vcc
	v_add_f32_e32 v70, v70, v71
	v_add_f32_e32 v71, v81, v82
	v_add_f32_e32 v75, v83, v84
	v_add_f32_e32 v71, v71, v75
	v_add_f32_e32 v75, v85, v86
	v_add_f32_e32 v76, v87, v88
	v_add_f32_e32 v75, v75, v76
	s_waitcnt vmcnt(1)
	v_mfma_f32_16x16x32_bf16 v[76:79], v[60:63], v[12:15], v[20:23]
	v_add_f32_e32 v71, v71, v75
	v_add_f32_e32 v70, v70, v71
	v_add_f32_e32 v70, v68, v70
	v_mfma_f32_16x16x32_bf16 v[80:83], v[52:55], v[12:15], v[20:23]
	v_mfma_f32_16x16x32_bf16 v[84:87], v[44:47], v[12:15], v[20:23]
	s_waitcnt vmcnt(0)
	v_mfma_f32_16x16x32_bf16 v[76:79], v[56:59], v[16:19], v[76:79]
	v_mfma_f32_16x16x32_bf16 v[88:91], v[36:39], v[12:15], v[20:23]
	v_mfma_f32_16x16x32_bf16 v[80:83], v[48:51], v[16:19], v[80:83]
	s_nop 5
	v_exp_f32_e32 v71, v76
	v_exp_f32_e32 v75, v77
	v_exp_f32_e32 v76, v78
	v_mfma_f32_16x16x32_bf16 v[84:87], v[40:43], v[16:19], v[84:87]
	v_exp_f32_e32 v77, v79
	v_exp_f32_e32 v78, v80
	v_exp_f32_e32 v79, v81
	v_mfma_f32_16x16x32_bf16 v[88:91], v[32:35], v[16:19], v[88:91]
	v_exp_f32_e32 v80, v82
	v_exp_f32_e32 v81, v83
	s_nop 1
	v_exp_f32_e32 v82, v84
	v_exp_f32_e32 v83, v85
	v_exp_f32_e32 v84, v86
	v_exp_f32_e32 v85, v87
	v_cndmask_b32_e64 v71, 0, v71, s[64:65]
	v_cndmask_b32_e64 v75, 0, v75, s[62:63]
	v_cndmask_b32_e64 v76, 0, v76, s[60:61]
	v_cndmask_b32_e64 v77, 0, v77, s[56:57]
	v_exp_f32_e32 v86, v88
	v_exp_f32_e32 v87, v89
	v_exp_f32_e32 v88, v90
	v_exp_f32_e32 v89, v91
	v_cndmask_b32_e64 v78, 0, v78, s[58:59]
	v_cndmask_b32_e64 v79, 0, v79, s[54:55]
	v_cndmask_b32_e64 v80, 0, v80, s[52:53]
	v_cndmask_b32_e64 v81, 0, v81, s[48:49]
	v_add_f32_e32 v71, v71, v75
	v_add_f32_e32 v75, v76, v77
	v_add_f32_e32 v71, v71, v75
	v_add_f32_e32 v75, v78, v79
	v_add_f32_e32 v76, v80, v81
	v_cndmask_b32_e64 v82, 0, v82, s[50:51]
	v_cndmask_b32_e64 v83, 0, v83, s[46:47]
	v_cndmask_b32_e64 v84, 0, v84, s[44:45]
	v_cndmask_b32_e64 v85, 0, v85, s[40:41]
	v_add_f32_e32 v75, v75, v76
	v_cndmask_b32_e64 v86, 0, v86, s[42:43]
	v_cndmask_b32_e64 v87, 0, v87, s[38:39]
	v_cndmask_b32_e64 v88, 0, v88, s[36:37]
	v_cndmask_b32_e32 v89, 0, v89, vcc
	v_add_f32_e32 v71, v71, v75
	v_add_f32_e32 v75, v82, v83
	v_add_f32_e32 v76, v84, v85
	v_add_f32_e32 v75, v75, v76
	v_add_f32_e32 v76, v86, v87
	v_add_f32_e32 v77, v88, v89
	v_add_f32_e32 v76, v76, v77
	v_add_f32_e32 v75, v75, v76
	v_add_f32_e32 v71, v71, v75
	s_cbranch_execnz .LBB0_131
	.p2align	6

.LBB0_142:
	s_lshl_b32 s60, s26, 1
	s_bitcmp1_b32 s26, 0
	s_cselect_b32 s0, 0x9000, 0
	s_add_i32 s61, s0, 0
	s_andn2_b32 s0, 1, s26
	s_mul_i32 s0, s0, 0x9000
	v_mov_b64_e32 v[32:33], v[108:109]
	v_mov_b64_e32 v[36:37], v[124:125]
	v_mov_b64_e32 v[40:41], v[104:105]
	v_mov_b64_e32 v[44:45], v[120:121]
	v_mov_b64_e32 v[48:49], v[100:101]
	v_mov_b64_e32 v[52:53], v[116:117]
	v_mov_b64_e32 v[56:57], v[96:97]
	v_mov_b64_e32 v[60:61], v[112:113]
	v_add_u32_e32 v0, s0, v177
	s_mov_b64 s[8:9], -1
	v_mov_b64_e32 v[34:35], v[110:111]
	v_mov_b64_e32 v[38:39], v[126:127]
	v_mov_b64_e32 v[42:43], v[106:107]
	v_mov_b64_e32 v[46:47], v[122:123]
	v_mov_b64_e32 v[50:51], v[102:103]
	v_mov_b64_e32 v[54:55], v[118:119]
	v_mov_b64_e32 v[58:59], v[98:99]
	v_mov_b64_e32 v[62:63], v[114:115]
	s_mov_b32 s2, 0
	s_branch .LBB0_144
	.p2align	6

.LBB0_148:
	s_lshl_b32 s2, s3, 6
	s_add_i32 s3, s61, s0
	v_add3_u32 v2, s3, v229, v230
	s_waitcnt lgkmcnt(8)
	ds_read_b128 v[92:95], v2
	s_waitcnt lgkmcnt(8)
	ds_read_b128 v[88:91], v2 offset:64
	s_waitcnt lgkmcnt(8)
	ds_read_b128 v[84:87], v2 offset:2304
	s_waitcnt lgkmcnt(8)
	ds_read_b128 v[80:83], v2 offset:2368
	s_waitcnt lgkmcnt(8)
	ds_read_b128 v[76:79], v2 offset:4608
	s_waitcnt lgkmcnt(8)
	ds_read_b128 v[72:75], v2 offset:4672
	s_waitcnt lgkmcnt(8)
	ds_read_b128 v[68:71], v2 offset:6912
	s_waitcnt lgkmcnt(8)
	ds_read_b128 v[64:67], v2 offset:6976
	s_or_b32 s14, s2, 63
	s_max_u32 s14, s2, s14
	v_add3_u32 v2, s3, v232, v230
	v_cmp_ge_u32_e32 vcc, s14, v174
	v_add_u32_e32 v236, s2, v233
	v_add_u32_e32 v240, 0x2000, v2
	v_add_u32_e32 v239, 0x2800, v2
	v_add_u32_e32 v238, 0x3000, v2
	v_add_u32_e32 v237, 0x3800, v2
	s_cbranch_vccz .LBB0_153
	v_add_u32_e32 v2, s2, v231
	v_or_b32_e32 v3, 1, v2
	v_cmp_lt_u32_e64 s[56:57], v3, v174
	v_or_b32_e32 v3, 2, v2
	v_cmp_lt_u32_e64 s[54:55], v3, v174
	v_or_b32_e32 v3, 3, v2
	v_cmp_lt_u32_e64 s[50:51], v3, v174
	v_add_u32_e32 v3, 16, v2
	s_waitcnt lgkmcnt(7)
	v_mfma_f32_16x16x32_bf16 v[96:99], v[92:95], v[4:7], v[20:23]
	v_cmp_lt_u32_e64 s[52:53], v3, v174
	v_add_u32_e32 v3, 17, v2
	v_cmp_lt_u32_e64 s[48:49], v3, v174
	v_add_u32_e32 v3, 18, v2
	v_cmp_lt_u32_e64 s[46:47], v3, v174
	v_add_u32_e32 v3, 19, v2
	v_cmp_lt_u32_e64 s[42:43], v3, v174
	v_add_u32_e32 v3, 32, v2
	s_waitcnt lgkmcnt(6)
	v_mfma_f32_16x16x32_bf16 v[96:99], v[88:91], v[8:11], v[96:99]
	v_cmp_lt_u32_e64 s[44:45], v3, v174
	v_add_u32_e32 v3, 33, v2
	v_cmp_lt_u32_e64 s[40:41], v3, v174
	v_add_u32_e32 v3, 34, v2
	v_cmp_lt_u32_e64 s[38:39], v3, v174
	v_add_u32_e32 v3, 35, v2
	v_cmp_lt_u32_e32 vcc, v3, v174
	s_nop 0
	v_exp_f32_e32 v3, v96
	v_cmp_lt_u32_e64 s[58:59], v2, v174
	s_waitcnt lgkmcnt(5)
	v_mfma_f32_16x16x32_bf16 v[100:103], v[84:87], v[4:7], v[20:23]
	v_cndmask_b32_e64 v96, 0, v3, s[58:59]
	v_exp_f32_e32 v3, v97
	s_waitcnt lgkmcnt(4)
	v_mfma_f32_16x16x32_bf16 v[100:103], v[80:83], v[8:11], v[100:103]
	v_fma_f32 v249, v182, v96, 0
	v_cndmask_b32_e64 v97, 0, v3, s[56:57]
	v_exp_f32_e32 v3, v98
	s_waitcnt lgkmcnt(3)
	v_mfma_f32_16x16x32_bf16 v[104:107], v[76:79], v[4:7], v[20:23]
	v_fma_f32 v250, v182, v97, 0
	v_cndmask_b32_e64 v98, 0, v3, s[54:55]
	v_exp_f32_e32 v3, v99
	s_waitcnt lgkmcnt(2)
	v_mfma_f32_16x16x32_bf16 v[104:107], v[72:75], v[8:11], v[104:107]
	v_fma_f32 v251, v182, v98, 0
	v_cndmask_b32_e64 v99, 0, v3, s[50:51]
	v_exp_f32_e32 v3, v100
	s_waitcnt lgkmcnt(1)
	v_mfma_f32_16x16x32_bf16 v[108:111], v[68:71], v[4:7], v[20:23]
	v_fma_f32 v248, v182, v99, 0
	v_cndmask_b32_e64 v100, 0, v3, s[52:53]
	v_exp_f32_e32 v3, v101
	s_waitcnt lgkmcnt(0)
	v_mfma_f32_16x16x32_bf16 v[108:111], v[64:67], v[8:11], v[108:111]
	v_fma_f32 v245, v182, v100, 0
	v_cndmask_b32_e64 v101, 0, v3, s[48:49]
	v_exp_f32_e32 v3, v102
	v_fma_f32 v246, v182, v101, 0
	s_nop 3
	v_exp_f32_e32 v115, v108
	v_mul_f32_e32 v108, v182, v96
	v_cndmask_b32_e64 v102, 0, v3, s[46:47]
	v_exp_f32_e32 v3, v103
	v_mul_f32_e32 v96, v182, v97
	v_mul_f32_e32 v97, v182, v98
	v_mul_f32_e32 v98, v182, v99
	v_cndmask_b32_e64 v103, 0, v3, s[42:43]
	v_exp_f32_e32 v3, v104
	v_mul_f32_e32 v99, v182, v100
	v_mul_f32_e32 v100, v182, v101
	v_mul_f32_e32 v101, v182, v102
	v_cndmask_b32_e64 v104, 0, v3, s[44:45]
	v_exp_f32_e32 v3, v105
	v_fma_f32 v247, v182, v102, 0
	v_mul_f32_e32 v102, v182, v103
	v_fma_f32 v241, v182, v103, 0
	v_cndmask_b32_e64 v105, 0, v3, s[40:41]
	v_exp_f32_e32 v3, v106
	v_mul_f32_e32 v103, v182, v104
	v_fma_f32 v131, v182, v104, 0
	v_mul_f32_e32 v104, v182, v105
	v_cndmask_b32_e64 v106, 0, v3, s[38:39]
	v_exp_f32_e32 v3, v107
	v_fma_f32 v242, v182, v105, 0
	v_mul_f32_e32 v105, v182, v106
	v_fma_f32 v243, v182, v106, 0
	v_cndmask_b32_e32 v107, 0, v3, vcc
	v_mul_f32_e32 v106, v182, v107
	v_exp_f32_e32 v114, v109
	v_exp_f32_e32 v130, v110
	v_exp_f32_e32 v3, v111
	v_fma_f32 v244, v182, v107, 0
	v_cvt_pk_bf16_f32 v96, v108, v96
	v_cvt_pk_bf16_f32 v97, v97, v98
	v_cvt_pk_bf16_f32 v98, v99, v100
	v_cvt_pk_bf16_f32 v99, v101, v102
	v_cvt_pk_bf16_f32 v108, v103, v104
	v_cvt_pk_bf16_f32 v109, v105, v106
	v_mfma_f32_16x16x32_bf16 v[100:103], v[92:95], v[12:15], v[20:23]
	v_mfma_f32_16x16x32_bf16 v[104:107], v[84:87], v[12:15], v[20:23]
	v_mfma_f32_16x16x32_bf16 v[110:113], v[76:79], v[12:15], v[20:23]
	s_waitcnt vmcnt(0)
	v_mfma_f32_16x16x32_bf16 v[100:103], v[88:91], v[16:19], v[100:103]
	v_mfma_f32_16x16x32_bf16 v[104:107], v[80:83], v[16:19], v[104:107]
	v_mfma_f32_16x16x32_bf16 v[110:113], v[72:75], v[16:19], v[110:113]
	s_nop 5
	v_exp_f32_e32 v100, v100
	v_exp_f32_e32 v101, v101
	v_exp_f32_e32 v102, v102
	v_mfma_f32_16x16x32_bf16 v[116:119], v[68:71], v[12:15], v[20:23]
	v_exp_f32_e32 v103, v103
	v_exp_f32_e32 v104, v104
	v_exp_f32_e32 v105, v105
	v_exp_f32_e32 v106, v106
	v_exp_f32_e32 v107, v107
	v_exp_f32_e32 v110, v110
	v_exp_f32_e32 v111, v111
	v_mfma_f32_16x16x32_bf16 v[116:119], v[64:67], v[16:19], v[116:119]
	v_exp_f32_e32 v112, v112
	v_exp_f32_e32 v113, v113
	v_cndmask_b32_e64 v100, 0, v100, s[58:59]
	v_cndmask_b32_e64 v101, 0, v101, s[56:57]
	v_cndmask_b32_e64 v102, 0, v102, s[54:55]
	v_cndmask_b32_e64 v103, 0, v103, s[50:51]
	v_cndmask_b32_e64 v104, 0, v104, s[52:53]
	v_cndmask_b32_e64 v105, 0, v105, s[48:49]
	v_cndmask_b32_e64 v106, 0, v106, s[46:47]
	v_cndmask_b32_e64 v107, 0, v107, s[42:43]
	v_cndmask_b32_e64 v110, 0, v110, s[44:45]
	v_cndmask_b32_e64 v111, 0, v111, s[40:41]
	v_cndmask_b32_e64 v112, 0, v112, s[38:39]
	v_cndmask_b32_e32 v113, 0, v113, vcc
	v_exp_f32_e32 v198, v116
	v_exp_f32_e32 v199, v117
	v_mul_f32_e32 v116, v183, v100
	v_fmac_f32_e32 v249, v183, v100
	v_mul_f32_e32 v100, v183, v101
	v_fmac_f32_e32 v250, v183, v101
	v_mul_f32_e32 v101, v183, v102
	v_fmac_f32_e32 v251, v183, v102
	v_mul_f32_e32 v102, v183, v103
	v_fmac_f32_e32 v248, v183, v103
	v_mul_f32_e32 v103, v183, v104
	v_fmac_f32_e32 v245, v183, v104
	v_mul_f32_e32 v104, v183, v105
	v_fmac_f32_e32 v246, v183, v105
	v_mul_f32_e32 v105, v183, v106
	v_fmac_f32_e32 v247, v183, v106
	v_mul_f32_e32 v106, v183, v107
	v_fmac_f32_e32 v241, v183, v107
	v_mul_f32_e32 v107, v183, v110
	v_mul_f32_e32 v117, v183, v111
	v_exp_f32_e32 v252, v118
	v_exp_f32_e32 v193, v119
	v_mul_f32_e32 v118, v183, v112
	v_fmac_f32_e32 v243, v183, v112
	v_mul_f32_e32 v119, v183, v113
	v_fmac_f32_e32 v244, v183, v113
	v_cvt_pk_bf16_f32 v112, v103, v104
	v_cvt_pk_bf16_f32 v113, v105, v106
	v_cvt_pk_bf16_f32 v128, v107, v117
	ds_read_b64 v[104:105], v240 offset:1024
	ds_read_b64 v[106:107], v240 offset:1056
	ds_read_b64 v[120:121], v239 offset:1280
	ds_read_b64 v[122:123], v239 offset:1312
	ds_read_b64 v[132:133], v238 offset:1536
	ds_read_b64 v[134:135], v238 offset:1568
	ds_read_b64 v[140:141], v237 offset:1792
	ds_read_b64 v[142:143], v237 offset:1824
	v_fmac_f32_e32 v131, v183, v110
	v_fmac_f32_e32 v242, v183, v111
	v_cvt_pk_bf16_f32 v110, v116, v100
	v_cvt_pk_bf16_f32 v111, v101, v102
	v_cvt_pk_bf16_f32 v129, v118, v119
	s_waitcnt lgkmcnt(6)
	v_mfma_f32_16x16x32_bf16 v[100:103], v[104:107], v[96:99], v[60:63]
	v_mfma_f32_16x16x32_bf16 v[104:107], v[104:107], v[110:113], v[56:59]
	s_waitcnt lgkmcnt(4)
	v_mfma_f32_16x16x32_bf16 v[116:119], v[120:123], v[96:99], v[52:55]
	v_mfma_f32_16x16x32_bf16 v[120:123], v[120:123], v[110:113], v[48:51]
	s_waitcnt lgkmcnt(2)
	v_mfma_f32_16x16x32_bf16 v[124:127], v[132:135], v[96:99], v[44:47]
	v_mfma_f32_16x16x32_bf16 v[132:135], v[132:135], v[110:113], v[40:43]
	s_waitcnt lgkmcnt(0)
	v_mfma_f32_16x16x32_bf16 v[136:139], v[140:143], v[96:99], v[36:39]
	ds_read_b64 v[96:97], v240 offset:1088
	ds_read_b64 v[98:99], v240 offset:1120
	ds_read_b64 v[152:153], v239 offset:1344
	ds_read_b64 v[154:155], v239 offset:1376
	ds_read_b64 v[148:149], v238 offset:1600
	ds_read_b64 v[150:151], v238 offset:1632
	ds_read_b64 v[144:145], v237 offset:1856
	ds_read_b64 v[146:147], v237 offset:1888
	v_mfma_f32_16x16x32_bf16 v[140:143], v[140:143], v[110:113], v[32:35]
	v_add_f32_e32 v110, v249, v250
	v_add_f32_e32 v111, v251, v248
	v_add_f32_e32 v110, v110, v111
	ds_bpermute_b32 v111, v234, v248
	ds_bpermute_b32 v112, v234, v235
	v_add_f32_e32 v113, v247, v241
	s_waitcnt lgkmcnt(0)
	v_cndmask_b32_e64 v112, v111, v112, s[36:37]
	v_add_f32_e32 v110, v110, v112
	v_add_f32_e32 v112, v245, v246
	v_add_f32_e32 v112, v112, v113
	ds_bpermute_b32 v113, v234, v241
	ds_bpermute_b32 v241, v234, v244
	s_waitcnt lgkmcnt(1)
	v_cndmask_b32_e64 v111, v113, v111, s[36:37]
	v_add_f32_e32 v111, v112, v111
	ds_write2_b32 v236, v110, v111 offset1:4
	v_add_f32_e32 v110, v131, v242
	v_add_f32_e32 v111, v243, v244
	v_add_f32_e32 v110, v110, v111
	s_waitcnt lgkmcnt(1)
	v_cndmask_b32_e64 v111, v241, v113, s[36:37]
	v_add_f32_e32 v110, v110, v111
	ds_write_b32 v236, v110 offset:32
	v_add_u32_e32 v110, 50, v2
	v_add_u32_e32 v111, 48, v2
	v_cmp_lt_u32_e64 s[38:39], v110, v171
	v_add_u32_e32 v110, 49, v2
	v_add_u32_e32 v2, 51, v2
	v_cmp_lt_u32_e32 vcc, v111, v174
	v_cmp_lt_u32_e64 s[40:41], v2, v171
	v_cmp_lt_u32_e64 s[42:43], v110, v174
	v_cndmask_b32_e64 v111, 0, v130, s[38:39]
	v_cndmask_b32_e32 v110, 0, v115, vcc
	v_cndmask_b32_e64 v2, 0, v114, s[42:43]
	v_cndmask_b32_e64 v3, 0, v3, s[40:41]
	v_pk_mul_f32 v[112:113], v[184:185], v[110:111]
	v_pk_fma_f32 v[114:115], v[184:185], v[110:111], 0 op_sel_hi:[1,1,0]
	v_pk_mul_f32 v[110:111], v[184:185], v[2:3]
	v_cndmask_b32_e64 v130, 0, v199, s[42:43]
	v_cvt_pk_bf16_f32 v110, v112, v110
	v_cvt_pk_bf16_f32 v111, v113, v111
	v_cndmask_b32_e64 v113, 0, v252, s[38:39]
	v_cndmask_b32_e32 v112, 0, v198, vcc
	v_cndmask_b32_e64 v131, 0, v193, s[40:41]
	v_pk_fma_f32 v[2:3], v[184:185], v[2:3], 0 op_sel_hi:[1,1,0]
	v_pk_mul_f32 v[198:199], v[186:187], v[112:113]
	v_pk_fma_f32 v[242:243], v[186:187], v[112:113], v[114:115]
	v_pk_mul_f32 v[112:113], v[186:187], v[130:131]
	v_pk_fma_f32 v[2:3], v[186:187], v[130:131], v[2:3]
	v_cvt_pk_bf16_f32 v130, v198, v112
	v_cvt_pk_bf16_f32 v131, v199, v113
	v_mfma_f32_16x16x32_bf16 v[112:115], v[96:99], v[108:111], v[100:103]
	s_nop 0
	v_mfma_f32_16x16x32_bf16 v[96:99], v[96:99], v[128:131], v[104:107]
	v_mfma_f32_16x16x32_bf16 v[116:119], v[152:155], v[108:111], v[116:119]
	v_mfma_f32_16x16x32_bf16 v[100:103], v[152:155], v[128:131], v[120:123]
	v_mfma_f32_16x16x32_bf16 v[120:123], v[148:151], v[108:111], v[124:127]
	v_mfma_f32_16x16x32_bf16 v[104:107], v[148:151], v[128:131], v[132:135]
	v_mfma_f32_16x16x32_bf16 v[124:127], v[144:147], v[108:111], v[136:139]
	v_mfma_f32_16x16x32_bf16 v[108:111], v[144:147], v[128:131], v[140:143]
	v_add_f32_e64 v128, v242, v2
	v_add_f32_e64 v129, v243, v3
	v_add_f32_e32 v2, v128, v129
	ds_bpermute_b32 v128, v234, v3
	s_waitcnt lgkmcnt(0)
	v_cndmask_b32_e64 v128, v128, v241, s[36:37]
	s_cbranch_execnz .LBB0_151
	.p2align	6

.LBB0_189:
	s_lshl_b32 s13, s3, 1
	s_bitcmp1_b32 s3, 0
	s_cselect_b32 s0, 0x9000, 0
	s_add_i32 s15, s0, 0
	s_andn2_b32 s0, 1, s3
	s_mul_i32 s0, s0, 0x9000
	v_mov_b64_e32 v[42:43], v[34:35]
	v_mov_b64_e32 v[44:45], v[80:81]
	v_mov_b64_e32 v[50:51], v[38:39]
	v_mov_b64_e32 v[52:53], v[92:93]
	v_mov_b64_e32 v[56:57], v[64:65]
	v_mov_b64_e32 v[68:69], v[88:89]
	v_mov_b64_e32 v[74:75], v[62:63]
	v_mov_b64_e32 v[76:77], v[84:85]
	v_add_u32_e32 v0, s0, v129
	s_mov_b64 s[92:93], -1
	v_mov_b64_e32 v[40:41], v[32:33]
	v_mov_b64_e32 v[46:47], v[82:83]
	v_mov_b64_e32 v[48:49], v[36:37]
	v_mov_b64_e32 v[54:55], v[94:95]
	v_mov_b64_e32 v[58:59], v[66:67]
	v_mov_b64_e32 v[70:71], v[90:91]
	v_mov_b64_e32 v[72:73], v[60:61]
	v_mov_b64_e32 v[78:79], v[86:87]
	s_mov_b32 s30, 0
	s_branch .LBB0_191
	.p2align	6

.LBB0_195:
	s_add_i32 s30, s15, s0
	v_add3_u32 v32, s30, v138, v139
	s_waitcnt lgkmcnt(7)
	ds_read_b128 v[124:127], v32
	s_waitcnt lgkmcnt(7)
	ds_read_b128 v[120:123], v32 offset:64
	s_waitcnt lgkmcnt(7)
	ds_read_b128 v[116:119], v32 offset:2304
	s_waitcnt lgkmcnt(7)
	ds_read_b128 v[96:99], v32 offset:2368
	s_waitcnt lgkmcnt(7)
	ds_read_b128 v[100:103], v32 offset:4608
	s_waitcnt lgkmcnt(7)
	ds_read_b128 v[104:107], v32 offset:4672
	s_waitcnt lgkmcnt(7)
	ds_read_b128 v[108:111], v32 offset:6912
	s_waitcnt lgkmcnt(7)
	ds_read_b128 v[112:115], v32 offset:6976
	s_lshl_b32 s31, s31, 6
	s_add_i32 s31, s31, s12
	v_sub_u32_e32 v32, s31, v3
	v_cmp_lt_u32_e32 vcc, s96, v32
	s_cbranch_vccz .LBB0_200
	s_waitcnt lgkmcnt(7)
	v_mfma_f32_16x16x32_bf16 v[32:35], v[124:127], v[4:7], v[20:23]
	v_add_u32_e32 v64, s31, v140
	v_add_u32_e32 v80, 1, v64
	v_cmp_gt_u32_e64 s[58:59], s22, v64
	s_waitcnt lgkmcnt(6)
	v_mfma_f32_16x16x32_bf16 v[32:35], v[120:123], v[8:11], v[32:35]
	v_cmp_gt_u32_e64 s[56:57], s22, v80
	v_add_u32_e32 v81, 2, v64
	v_add_u32_e32 v82, 3, v64
	s_waitcnt lgkmcnt(5)
	v_mfma_f32_16x16x32_bf16 v[36:39], v[116:119], v[4:7], v[20:23]
	v_cmp_gt_u32_e64 s[60:61], s22, v81
	s_nop 1
	v_exp_f32_e32 v32, v32
	v_exp_f32_e32 v33, v33
	s_waitcnt lgkmcnt(4)
	v_mfma_f32_16x16x32_bf16 v[36:39], v[96:99], v[8:11], v[36:39]
	v_cmp_gt_u32_e64 s[62:63], s22, v82
	v_cndmask_b32_e64 v95, 0, v32, s[58:59]
	v_cndmask_b32_e64 v80, 0, v33, s[56:57]
	v_exp_f32_e32 v32, v34
	v_exp_f32_e32 v33, v35
	s_waitcnt lgkmcnt(3)
	v_mfma_f32_16x16x32_bf16 v[60:63], v[100:103], v[4:7], v[20:23]
	v_add_u32_e32 v83, 16, v64
	v_cndmask_b32_e64 v81, 0, v32, s[60:61]
	v_exp_f32_e32 v32, v36
	v_cndmask_b32_e64 v82, 0, v33, s[62:63]
	v_exp_f32_e32 v33, v37
	v_add_u32_e32 v84, 17, v64
	v_cmp_gt_u32_e64 s[64:65], s22, v83
	v_cmp_gt_u32_e64 s[48:49], s22, v84
	s_waitcnt lgkmcnt(2)
	v_mfma_f32_16x16x32_bf16 v[60:63], v[104:107], v[8:11], v[60:63]
	v_cndmask_b32_e64 v83, 0, v32, s[64:65]
	v_exp_f32_e32 v32, v38
	v_cndmask_b32_e64 v84, 0, v33, s[48:49]
	v_exp_f32_e32 v33, v39
	v_add_u32_e32 v85, 18, v64
	v_add_u32_e32 v86, 19, v64
	v_cmp_gt_u32_e64 s[50:51], s22, v85
	v_cmp_gt_u32_e64 s[52:53], s22, v86
	v_add_u32_e32 v87, 32, v64
	v_add_u32_e32 v88, 33, v64
	v_add_u32_e32 v89, 34, v64
	v_add_u32_e32 v90, 35, v64
	v_add_u32_e32 v91, 48, v64
	v_add_u32_e32 v92, 49, v64
	v_add_u32_e32 v93, 50, v64
	v_add_u32_e32 v94, 51, v64
	s_waitcnt lgkmcnt(1)
	v_mfma_f32_16x16x32_bf16 v[64:67], v[108:111], v[4:7], v[20:23]
	v_cndmask_b32_e64 v85, 0, v32, s[50:51]
	v_exp_f32_e32 v32, v60
	v_cndmask_b32_e64 v86, 0, v33, s[52:53]
	v_exp_f32_e32 v33, v61
	v_cmp_gt_u32_e64 s[54:55], s22, v87
	v_cmp_gt_u32_e64 s[40:41], s22, v88
	s_waitcnt lgkmcnt(0)
	v_mfma_f32_16x16x32_bf16 v[64:67], v[112:115], v[8:11], v[64:67]
	v_cndmask_b32_e64 v87, 0, v32, s[54:55]
	v_exp_f32_e32 v32, v62
	v_cndmask_b32_e64 v88, 0, v33, s[40:41]
	v_exp_f32_e32 v33, v63
	v_cmp_gt_u32_e32 vcc, s22, v89
	v_cmp_gt_u32_e64 s[38:39], s22, v90
	v_cmp_gt_u32_e64 s[46:47], s22, v91
	v_cndmask_b32_e32 v89, 0, v32, vcc
	v_exp_f32_e32 v32, v64
	v_cndmask_b32_e64 v90, 0, v33, s[38:39]
	v_exp_f32_e32 v33, v65
	v_cmp_gt_u32_e64 s[36:37], s22, v92
	v_cndmask_b32_e64 v91, 0, v32, s[46:47]
	v_exp_f32_e32 v32, v66
	v_cndmask_b32_e64 v92, 0, v33, s[36:37]
	v_exp_f32_e32 v33, v67
	v_cmp_gt_u32_e64 s[42:43], s22, v93
	v_cmp_gt_u32_e64 s[44:45], s22, v94
	v_add_f32_e32 v37, v83, v84
	v_cndmask_b32_e64 v93, 0, v32, s[42:43]
	v_cndmask_b32_e64 v94, 0, v33, s[44:45]
	v_add_f32_e32 v32, v95, v80
	v_add_f32_e32 v33, v81, v82
	v_add_f32_e32 v38, v85, v86
	v_add_f32_e32 v36, v32, v33
	v_add_f32_e32 v37, v37, v38
	v_mfma_f32_16x16x32_bf16 v[32:35], v[124:127], v[12:15], v[20:23]
	v_add_f32_e32 v60, v36, v37
	v_add_f32_e32 v36, v87, v88
	v_add_f32_e32 v37, v89, v90
	v_add_f32_e32 v62, v91, v92
	v_add_f32_e32 v63, v93, v94
	v_add_f32_e32 v61, v36, v37
	v_add_f32_e32 v62, v62, v63
	v_add_f32_e32 v61, v61, v62
	v_add_f32_e32 v60, v60, v61
	v_mfma_f32_16x16x32_bf16 v[32:35], v[120:123], v[16:19], v[32:35]
	v_add_f32_e32 v136, v134, v60
	v_add3_u32 v174, s30, v141, v139
	v_add_u32_e32 v227, 0x2800, v174
	v_mfma_f32_16x16x32_bf16 v[36:39], v[116:119], v[12:15], v[20:23]
	v_cvt_pk_bf16_f32 v64, v95, v80
	s_nop 2
	v_exp_f32_e32 v32, v32
	v_cvt_pk_bf16_f32 v65, v81, v82
	v_mfma_f32_16x16x32_bf16 v[60:63], v[100:103], v[12:15], v[20:23]
	v_cvt_pk_bf16_f32 v66, v83, v84
	v_cndmask_b32_e64 v137, 0, v32, s[58:59]
	v_exp_f32_e32 v32, v33
	v_mfma_f32_16x16x32_bf16 v[36:39], v[96:99], v[16:19], v[36:39]
	v_exp_f32_e32 v33, v34
	v_exp_f32_e32 v34, v35
	v_cvt_pk_bf16_f32 v67, v85, v86
	v_mfma_f32_16x16x32_bf16 v[60:63], v[104:107], v[16:19], v[60:63]
	v_cvt_pk_bf16_f32 v80, v87, v88
	s_nop 2
	v_exp_f32_e32 v35, v36
	v_exp_f32_e32 v36, v37
	v_exp_f32_e32 v37, v38
	v_exp_f32_e32 v38, v39
	v_exp_f32_e32 v39, v60
	v_exp_f32_e32 v60, v61
	v_cvt_pk_bf16_f32 v81, v89, v90
	v_mfma_f32_16x16x32_bf16 v[84:87], v[108:111], v[12:15], v[20:23]
	v_cvt_pk_bf16_f32 v82, v91, v92
	ds_read_b64 v[88:89], v227 offset:1280
	ds_read_b64 v[90:91], v227 offset:1312
	v_add_u32_e32 v180, 0x2000, v174
	v_add_u32_e32 v230, 0x3000, v174
	v_add_u32_e32 v174, 0x3800, v174
	v_cndmask_b32_e64 v143, 0, v32, s[56:57]
	v_cndmask_b32_e64 v171, 0, v33, s[60:61]
	v_cndmask_b32_e64 v172, 0, v34, s[62:63]
	v_cndmask_b32_e64 v173, 0, v35, s[64:65]
	ds_read_b64 v[32:33], v180 offset:1024
	ds_read_b64 v[34:35], v180 offset:1056
	ds_read_b64 v[144:145], v230 offset:1536
	ds_read_b64 v[146:147], v230 offset:1568
	v_cndmask_b32_e64 v231, 0, v60, s[40:41]
	v_exp_f32_e32 v181, v62
	v_exp_f32_e32 v182, v63
	ds_read_b64 v[60:61], v174 offset:1792
	ds_read_b64 v[62:63], v174 offset:1824
	v_mfma_f32_16x16x32_bf16 v[84:87], v[112:115], v[16:19], v[84:87]
	v_cndmask_b32_e64 v193, 0, v36, s[48:49]
	v_cndmask_b32_e64 v198, 0, v37, s[50:51]
	v_cndmask_b32_e64 v199, 0, v38, s[52:53]
	v_cndmask_b32_e64 v225, 0, v39, s[54:55]
	v_cvt_pk_bf16_f32 v36, v137, v143
	v_cvt_pk_bf16_f32 v37, v171, v172
	v_cvt_pk_bf16_f32 v38, v173, v193
	v_cvt_pk_bf16_f32 v39, v198, v199
	v_exp_f32_e32 v84, v84
	s_waitcnt lgkmcnt(6)
	v_mfma_f32_16x16x32_bf16 v[148:151], v[88:91], v[64:67], v[68:71]
	v_cvt_pk_bf16_f32 v83, v93, v94
	v_cndmask_b32_e32 v232, 0, v181, vcc
	v_cndmask_b32_e64 v233, 0, v182, s[38:39]
	v_mfma_f32_16x16x32_bf16 v[152:155], v[88:91], v[36:39], v[56:59]
	ds_read_b64 v[88:89], v180 offset:1088
	ds_read_b64 v[90:91], v180 offset:1120
	v_cndmask_b32_e64 v234, 0, v84, s[46:47]
	v_exp_f32_e32 v84, v85
	s_waitcnt lgkmcnt(6)
	v_mfma_f32_16x16x32_bf16 v[92:95], v[32:35], v[64:67], v[76:79]
	v_exp_f32_e32 v85, v86
	v_cvt_pk_bf16_f32 v226, v225, v231
	v_cndmask_b32_e64 v235, 0, v84, s[36:37]
	s_waitcnt lgkmcnt(4)
	v_mfma_f32_16x16x32_bf16 v[176:179], v[144:147], v[64:67], v[52:55]
	v_cndmask_b32_e64 v236, 0, v85, s[42:43]
	v_cvt_pk_bf16_f32 v228, v234, v235
	s_waitcnt lgkmcnt(2)
	v_mfma_f32_16x16x32_bf16 v[180:183], v[60:63], v[64:67], v[44:47]
	v_exp_f32_e32 v64, v87
	v_add_f32_e32 v65, v171, v172
	v_cndmask_b32_e64 v237, 0, v64, s[44:45]
	v_mfma_f32_16x16x32_bf16 v[32:35], v[32:35], v[36:39], v[72:75]
	v_cvt_pk_bf16_f32 v229, v236, v237
	v_add_f32_e32 v64, v137, v143
	v_mfma_f32_16x16x32_bf16 v[144:147], v[144:147], v[36:39], v[48:51]
	v_mfma_f32_16x16x32_bf16 v[184:187], v[60:63], v[36:39], v[40:43]
	ds_read_b64 v[36:37], v227 offset:1344
	ds_read_b64 v[38:39], v227 offset:1376
	v_cvt_pk_bf16_f32 v227, v232, v233
	s_waitcnt lgkmcnt(2)
	v_mfma_f32_16x16x32_bf16 v[84:87], v[88:91], v[80:83], v[92:95]
	v_mfma_f32_16x16x32_bf16 v[60:63], v[88:91], v[226:229], v[32:35]
	s_nop 1
	v_add_f32_e32 v93, v173, v193
	v_add_f32_e32 v94, v198, v199
	v_add_f32_e32 v92, v64, v65
	ds_read_b64 v[32:33], v230 offset:1600
	ds_read_b64 v[34:35], v230 offset:1632
	s_waitcnt lgkmcnt(2)
	v_mfma_f32_16x16x32_bf16 v[88:91], v[36:39], v[80:83], v[148:151]
	s_nop 2
	ds_read_b64 v[148:149], v174 offset:1856
	ds_read_b64 v[150:151], v174 offset:1888
	v_mfma_f32_16x16x32_bf16 v[64:67], v[36:39], v[226:229], v[152:155]
	v_add_f32_e32 v36, v93, v94
	v_add_f32_e32 v137, v92, v36
	v_add_f32_e32 v36, v225, v231
	v_add_f32_e32 v37, v232, v233
	s_waitcnt lgkmcnt(2)
	v_mfma_f32_16x16x32_bf16 v[92:95], v[32:35], v[80:83], v[176:179]
	v_add_f32_e32 v143, v36, v37
	v_mfma_f32_16x16x32_bf16 v[36:39], v[32:35], v[226:229], v[144:147]
	v_add_f32_e32 v32, v234, v235
	v_add_f32_e32 v33, v236, v237
	v_add_f32_e32 v32, v32, v33
	v_add_f32_e32 v32, v143, v32
	v_add_f32_e32 v32, v137, v32
	s_waitcnt lgkmcnt(0)
	v_mfma_f32_16x16x32_bf16 v[80:83], v[148:151], v[80:83], v[180:183]
	v_add_f32_e32 v137, v135, v32
	v_mfma_f32_16x16x32_bf16 v[32:35], v[148:151], v[226:229], v[184:187]
	s_cbranch_execnz .LBB0_198
	.p2align	6

.LBB0_206:
	s_lshl_b32 s30, s94, 1
	s_bitcmp1_b32 s94, 0
	s_cselect_b32 s0, 0x9000, 0
	s_andn2_b32 s2, 1, s94
	s_mul_i32 s2, s2, 0x9000
	v_add_u32_e32 v0, s0, v73
	v_add_u32_e32 v74, s2, v72
	s_mov_b64 s[2:3], -1
	s_mov_b32 s31, 0
	s_branch .LBB0_208
	.p2align	6

.LBB0_212:
	s_waitcnt lgkmcnt(0)
	v_add_u32_e32 v32, s0, v0
	ds_read_b128 v[60:63], v32
	ds_read_b128 v[56:59], v32 offset:64
	ds_read_b128 v[52:55], v32 offset:2304
	ds_read_b128 v[48:51], v32 offset:2368
	ds_read_b128 v[44:47], v32 offset:4608
	ds_read_b128 v[40:43], v32 offset:4672
	ds_read_b128 v[36:39], v32 offset:6912
	ds_read_b128 v[32:35], v32 offset:6976
	s_lshl_b32 s31, s36, 6
	s_or_b32 s36, s31, 63
	s_max_u32 s36, s31, s36
	v_cmp_ge_u32_e32 vcc, s36, v174
	s_cbranch_vccz .LBB0_217
	v_add_u32_e32 v70, s31, v3
	v_or_b32_e32 v71, 1, v70
	v_cmp_lt_u32_e64 s[62:63], v71, v174
	v_or_b32_e32 v71, 2, v70
	v_cmp_lt_u32_e64 s[60:61], v71, v174
	v_or_b32_e32 v71, 3, v70
	v_cmp_lt_u32_e64 s[56:57], v71, v174
	v_add_u32_e32 v71, 16, v70
	v_cmp_lt_u32_e64 s[58:59], v71, v174
	v_add_u32_e32 v71, 17, v70
	v_cmp_lt_u32_e64 s[54:55], v71, v174
	v_add_u32_e32 v71, 18, v70
	v_cmp_lt_u32_e64 s[52:53], v71, v174
	v_add_u32_e32 v71, 19, v70
	s_waitcnt lgkmcnt(7)
	v_mfma_f32_16x16x32_bf16 v[76:79], v[60:63], v[4:7], v[20:23]
	v_cmp_lt_u32_e64 s[48:49], v71, v174
	v_add_u32_e32 v71, 32, v70
	v_cmp_lt_u32_e64 s[50:51], v71, v174
	s_waitcnt lgkmcnt(5)
	v_mfma_f32_16x16x32_bf16 v[80:83], v[52:55], v[4:7], v[20:23]
	v_add_u32_e32 v71, 33, v70
	v_cmp_lt_u32_e64 s[46:47], v71, v174
	v_add_u32_e32 v71, 34, v70
	s_waitcnt lgkmcnt(3)
	v_mfma_f32_16x16x32_bf16 v[84:87], v[44:47], v[4:7], v[20:23]
	v_cmp_lt_u32_e64 s[44:45], v71, v174
	v_add_u32_e32 v71, 35, v70
	v_cmp_lt_u32_e64 s[40:41], v71, v174
	v_mfma_f32_16x16x32_bf16 v[76:79], v[56:59], v[8:11], v[76:79]
	v_add_u32_e32 v71, 48, v70
	v_cmp_lt_u32_e64 s[42:43], v71, v174
	v_add_u32_e32 v71, 49, v70
	s_waitcnt lgkmcnt(1)
	v_mfma_f32_16x16x32_bf16 v[88:91], v[36:39], v[4:7], v[20:23]
	v_cmp_lt_u32_e64 s[64:65], v70, v174
	v_cmp_lt_u32_e64 s[38:39], v71, v174
	v_add_u32_e32 v71, 50, v70
	v_mfma_f32_16x16x32_bf16 v[80:83], v[48:51], v[8:11], v[80:83]
	v_add_u32_e32 v70, 51, v70
	v_cmp_lt_u32_e64 s[36:37], v71, v174
	v_cmp_lt_u32_e32 vcc, v70, v174
	v_mfma_f32_16x16x32_bf16 v[84:87], v[40:43], v[8:11], v[84:87]
	v_exp_f32_e32 v70, v76
	v_exp_f32_e32 v71, v77
	v_exp_f32_e32 v75, v78
	s_waitcnt lgkmcnt(0)
	v_mfma_f32_16x16x32_bf16 v[88:91], v[32:35], v[8:11], v[88:91]
	v_exp_f32_e32 v76, v79
	v_exp_f32_e32 v77, v80
	v_exp_f32_e32 v78, v81
	v_exp_f32_e32 v79, v82
	v_exp_f32_e32 v80, v83
	v_exp_f32_e32 v81, v84
	v_exp_f32_e32 v82, v85
	v_exp_f32_e32 v83, v86
	v_exp_f32_e32 v84, v87
	v_cndmask_b32_e64 v70, 0, v70, s[64:65]
	v_cndmask_b32_e64 v71, 0, v71, s[62:63]
	v_cndmask_b32_e64 v75, 0, v75, s[60:61]
	v_cndmask_b32_e64 v76, 0, v76, s[56:57]
	v_exp_f32_e32 v85, v88
	v_exp_f32_e32 v86, v89
	v_exp_f32_e32 v87, v90
	v_exp_f32_e32 v88, v91
	v_cndmask_b32_e64 v77, 0, v77, s[58:59]
	v_cndmask_b32_e64 v78, 0, v78, s[54:55]
	v_cndmask_b32_e64 v79, 0, v79, s[52:53]
	v_cndmask_b32_e64 v80, 0, v80, s[48:49]
	v_add_f32_e32 v70, v70, v71
	v_add_f32_e32 v71, v75, v76
	v_add_f32_e32 v70, v70, v71
	v_add_f32_e32 v71, v77, v78
	v_add_f32_e32 v75, v79, v80
	v_cndmask_b32_e64 v81, 0, v81, s[50:51]
	v_cndmask_b32_e64 v82, 0, v82, s[46:47]
	v_cndmask_b32_e64 v83, 0, v83, s[44:45]
	v_cndmask_b32_e64 v84, 0, v84, s[40:41]
	v_add_f32_e32 v71, v71, v75
	v_cndmask_b32_e64 v85, 0, v85, s[42:43]
	v_cndmask_b32_e64 v86, 0, v86, s[38:39]
	v_cndmask_b32_e64 v87, 0, v87, s[36:37]
	v_cndmask_b32_e32 v88, 0, v88, vcc
	v_add_f32_e32 v70, v70, v71
	v_add_f32_e32 v71, v81, v82
	v_add_f32_e32 v75, v83, v84
	v_add_f32_e32 v71, v71, v75
	v_add_f32_e32 v75, v85, v86
	v_add_f32_e32 v76, v87, v88
	v_add_f32_e32 v75, v75, v76
	v_mfma_f32_16x16x32_bf16 v[76:79], v[60:63], v[12:15], v[20:23]
	v_add_f32_e32 v71, v71, v75
	v_add_f32_e32 v70, v70, v71
	v_add_f32_e32 v70, v64, v70
	v_mfma_f32_16x16x32_bf16 v[80:83], v[52:55], v[12:15], v[20:23]
	v_mfma_f32_16x16x32_bf16 v[84:87], v[44:47], v[12:15], v[20:23]
	v_mfma_f32_16x16x32_bf16 v[76:79], v[56:59], v[16:19], v[76:79]
	v_mfma_f32_16x16x32_bf16 v[88:91], v[36:39], v[12:15], v[20:23]
	v_mfma_f32_16x16x32_bf16 v[80:83], v[48:51], v[16:19], v[80:83]
	s_nop 5
	v_exp_f32_e32 v71, v76
	v_exp_f32_e32 v75, v77
	v_exp_f32_e32 v76, v78
	v_mfma_f32_16x16x32_bf16 v[84:87], v[40:43], v[16:19], v[84:87]
	v_exp_f32_e32 v77, v79
	v_exp_f32_e32 v78, v80
	v_exp_f32_e32 v79, v81
	v_mfma_f32_16x16x32_bf16 v[88:91], v[32:35], v[16:19], v[88:91]
	v_exp_f32_e32 v80, v82
	v_exp_f32_e32 v81, v83
	s_nop 1
	v_exp_f32_e32 v82, v84
	v_exp_f32_e32 v83, v85
	v_exp_f32_e32 v84, v86
	v_exp_f32_e32 v85, v87
	v_cndmask_b32_e64 v71, 0, v71, s[64:65]
	v_cndmask_b32_e64 v75, 0, v75, s[62:63]
	v_cndmask_b32_e64 v76, 0, v76, s[60:61]
	v_cndmask_b32_e64 v77, 0, v77, s[56:57]
	v_exp_f32_e32 v86, v88
	v_exp_f32_e32 v87, v89
	v_exp_f32_e32 v88, v90
	v_exp_f32_e32 v89, v91
	v_cndmask_b32_e64 v78, 0, v78, s[58:59]
	v_cndmask_b32_e64 v79, 0, v79, s[54:55]
	v_cndmask_b32_e64 v80, 0, v80, s[52:53]
	v_cndmask_b32_e64 v81, 0, v81, s[48:49]
	v_add_f32_e32 v71, v71, v75
	v_add_f32_e32 v75, v76, v77
	v_add_f32_e32 v71, v71, v75
	v_add_f32_e32 v75, v78, v79
	v_add_f32_e32 v76, v80, v81
	v_cndmask_b32_e64 v82, 0, v82, s[50:51]
	v_cndmask_b32_e64 v83, 0, v83, s[46:47]
	v_cndmask_b32_e64 v84, 0, v84, s[44:45]
	v_cndmask_b32_e64 v85, 0, v85, s[40:41]
	v_add_f32_e32 v75, v75, v76
	v_cndmask_b32_e64 v86, 0, v86, s[42:43]
	v_cndmask_b32_e64 v87, 0, v87, s[38:39]
	v_cndmask_b32_e64 v88, 0, v88, s[36:37]
	v_cndmask_b32_e32 v89, 0, v89, vcc
	v_add_f32_e32 v71, v71, v75
	v_add_f32_e32 v75, v82, v83
	v_add_f32_e32 v76, v84, v85
	v_add_f32_e32 v75, v75, v76
	v_add_f32_e32 v76, v86, v87
	v_add_f32_e32 v77, v88, v89
	v_add_f32_e32 v76, v76, v77
	v_add_f32_e32 v75, v75, v76
	v_add_f32_e32 v71, v71, v75
	s_cbranch_execnz .LBB0_215
	.p2align	6

.LBB0_220:
	s_lshl_b32 s19, s18, 1
	s_bitcmp1_b32 s18, 0
	s_cselect_b32 s0, 0x9000, 0
	s_add_i32 s60, s0, 0
	s_andn2_b32 s0, 1, s18
	s_mul_i32 s0, s0, 0x9000
	v_mov_b64_e32 v[32:33], v[108:109]
	v_mov_b64_e32 v[36:37], v[124:125]
	v_mov_b64_e32 v[40:41], v[104:105]
	v_mov_b64_e32 v[44:45], v[120:121]
	v_mov_b64_e32 v[48:49], v[100:101]
	v_mov_b64_e32 v[52:53], v[116:117]
	v_mov_b64_e32 v[56:57], v[96:97]
	v_mov_b64_e32 v[60:61], v[112:113]
	v_add_u32_e32 v0, s0, v231
	s_mov_b64 s[2:3], -1
	v_mov_b64_e32 v[34:35], v[110:111]
	v_mov_b64_e32 v[38:39], v[126:127]
	v_mov_b64_e32 v[42:43], v[106:107]
	v_mov_b64_e32 v[46:47], v[122:123]
	v_mov_b64_e32 v[50:51], v[102:103]
	v_mov_b64_e32 v[54:55], v[118:119]
	v_mov_b64_e32 v[58:59], v[98:99]
	v_mov_b64_e32 v[62:63], v[114:115]
	s_mov_b32 s38, 0
	s_branch .LBB0_222
	.p2align	6

.LBB0_226:
	s_add_i32 s31, s60, s0
	v_add3_u32 v2, s31, v177, v228
	s_waitcnt lgkmcnt(8)
	ds_read_b128 v[92:95], v2
	s_waitcnt lgkmcnt(8)
	ds_read_b128 v[88:91], v2 offset:64
	s_waitcnt lgkmcnt(8)
	ds_read_b128 v[84:87], v2 offset:2304
	s_waitcnt lgkmcnt(8)
	ds_read_b128 v[80:83], v2 offset:2368
	s_waitcnt lgkmcnt(8)
	ds_read_b128 v[76:79], v2 offset:4608
	s_waitcnt lgkmcnt(8)
	ds_read_b128 v[72:75], v2 offset:4672
	s_waitcnt lgkmcnt(8)
	ds_read_b128 v[68:71], v2 offset:6912
	s_waitcnt lgkmcnt(8)
	ds_read_b128 v[64:67], v2 offset:6976
	s_lshl_b32 s30, s30, 6
	s_or_b32 s38, s30, 63
	s_max_u32 s38, s30, s38
	v_add3_u32 v2, s31, v230, v228
	v_cmp_ge_u32_e32 vcc, s38, v174
	v_add_u32_e32 v235, s30, v232
	v_add_u32_e32 v239, 0x2000, v2
	v_add_u32_e32 v238, 0x2800, v2
	v_add_u32_e32 v237, 0x3000, v2
	v_add_u32_e32 v236, 0x3800, v2
	s_cbranch_vccz .LBB0_231
	v_add_u32_e32 v2, s30, v229
	v_or_b32_e32 v3, 1, v2
	v_cmp_lt_u32_e64 s[56:57], v3, v174
	v_or_b32_e32 v3, 2, v2
	v_cmp_lt_u32_e64 s[54:55], v3, v174
	v_or_b32_e32 v3, 3, v2
	v_cmp_lt_u32_e64 s[50:51], v3, v174
	v_add_u32_e32 v3, 16, v2
	s_waitcnt lgkmcnt(7)
	v_mfma_f32_16x16x32_bf16 v[96:99], v[92:95], v[4:7], v[20:23]
	v_cmp_lt_u32_e64 s[52:53], v3, v174
	v_add_u32_e32 v3, 17, v2
	v_cmp_lt_u32_e64 s[48:49], v3, v174
	v_add_u32_e32 v3, 18, v2
	v_cmp_lt_u32_e64 s[46:47], v3, v174
	v_add_u32_e32 v3, 19, v2
	v_cmp_lt_u32_e64 s[42:43], v3, v174
	v_add_u32_e32 v3, 32, v2
	s_waitcnt lgkmcnt(6)
	v_mfma_f32_16x16x32_bf16 v[96:99], v[88:91], v[8:11], v[96:99]
	v_cmp_lt_u32_e64 s[44:45], v3, v174
	v_add_u32_e32 v3, 33, v2
	v_cmp_lt_u32_e64 s[40:41], v3, v174
	v_add_u32_e32 v3, 34, v2
	v_cmp_lt_u32_e64 s[38:39], v3, v174
	v_add_u32_e32 v3, 35, v2
	v_cmp_lt_u32_e32 vcc, v3, v174
	s_nop 0
	v_exp_f32_e32 v3, v96
	v_cmp_lt_u32_e64 s[58:59], v2, v174
	s_waitcnt lgkmcnt(5)
	v_mfma_f32_16x16x32_bf16 v[100:103], v[84:87], v[4:7], v[20:23]
	v_cndmask_b32_e64 v96, 0, v3, s[58:59]
	v_exp_f32_e32 v3, v97
	s_waitcnt lgkmcnt(4)
	v_mfma_f32_16x16x32_bf16 v[100:103], v[80:83], v[8:11], v[100:103]
	v_fma_f32 v248, v182, v96, 0
	v_cndmask_b32_e64 v97, 0, v3, s[56:57]
	v_exp_f32_e32 v3, v98
	s_waitcnt lgkmcnt(3)
	v_mfma_f32_16x16x32_bf16 v[104:107], v[76:79], v[4:7], v[20:23]
	v_fma_f32 v249, v182, v97, 0
	v_cndmask_b32_e64 v98, 0, v3, s[54:55]
	v_exp_f32_e32 v3, v99
	s_waitcnt lgkmcnt(2)
	v_mfma_f32_16x16x32_bf16 v[104:107], v[72:75], v[8:11], v[104:107]
	v_fma_f32 v250, v182, v98, 0
	v_cndmask_b32_e64 v99, 0, v3, s[50:51]
	v_exp_f32_e32 v3, v100
	s_waitcnt lgkmcnt(1)
	v_mfma_f32_16x16x32_bf16 v[108:111], v[68:71], v[4:7], v[20:23]
	v_fma_f32 v247, v182, v99, 0
	v_cndmask_b32_e64 v100, 0, v3, s[52:53]
	v_exp_f32_e32 v3, v101
	s_waitcnt lgkmcnt(0)
	v_mfma_f32_16x16x32_bf16 v[108:111], v[64:67], v[8:11], v[108:111]
	v_fma_f32 v244, v182, v100, 0
	v_cndmask_b32_e64 v101, 0, v3, s[48:49]
	v_exp_f32_e32 v3, v102
	v_fma_f32 v245, v182, v101, 0
	s_nop 3
	v_exp_f32_e32 v115, v108
	v_mul_f32_e32 v108, v182, v96
	v_cndmask_b32_e64 v102, 0, v3, s[46:47]
	v_exp_f32_e32 v3, v103
	v_mul_f32_e32 v96, v182, v97
	v_mul_f32_e32 v97, v182, v98
	v_mul_f32_e32 v98, v182, v99
	v_cndmask_b32_e64 v103, 0, v3, s[42:43]
	v_exp_f32_e32 v3, v104
	v_mul_f32_e32 v99, v182, v100
	v_mul_f32_e32 v100, v182, v101
	v_mul_f32_e32 v101, v182, v102
	v_cndmask_b32_e64 v104, 0, v3, s[44:45]
	v_exp_f32_e32 v3, v105
	v_fma_f32 v246, v182, v102, 0
	v_mul_f32_e32 v102, v182, v103
	v_fma_f32 v240, v182, v103, 0
	v_cndmask_b32_e64 v105, 0, v3, s[40:41]
	v_exp_f32_e32 v3, v106
	v_mul_f32_e32 v103, v182, v104
	v_fma_f32 v131, v182, v104, 0
	v_mul_f32_e32 v104, v182, v105
	v_cndmask_b32_e64 v106, 0, v3, s[38:39]
	v_exp_f32_e32 v3, v107
	v_fma_f32 v241, v182, v105, 0
	v_mul_f32_e32 v105, v182, v106
	v_fma_f32 v242, v182, v106, 0
	v_cndmask_b32_e32 v107, 0, v3, vcc
	v_mul_f32_e32 v106, v182, v107
	v_exp_f32_e32 v114, v109
	v_exp_f32_e32 v130, v110
	v_exp_f32_e32 v3, v111
	v_fma_f32 v243, v182, v107, 0
	v_cvt_pk_bf16_f32 v96, v108, v96
	v_cvt_pk_bf16_f32 v97, v97, v98
	v_cvt_pk_bf16_f32 v98, v99, v100
	v_cvt_pk_bf16_f32 v99, v101, v102
	v_cvt_pk_bf16_f32 v108, v103, v104
	v_cvt_pk_bf16_f32 v109, v105, v106
	v_mfma_f32_16x16x32_bf16 v[100:103], v[92:95], v[12:15], v[20:23]
	v_mfma_f32_16x16x32_bf16 v[104:107], v[84:87], v[12:15], v[20:23]
	v_mfma_f32_16x16x32_bf16 v[110:113], v[76:79], v[12:15], v[20:23]
	v_mfma_f32_16x16x32_bf16 v[100:103], v[88:91], v[16:19], v[100:103]
	v_mfma_f32_16x16x32_bf16 v[104:107], v[80:83], v[16:19], v[104:107]
	v_mfma_f32_16x16x32_bf16 v[110:113], v[72:75], v[16:19], v[110:113]
	s_nop 5
	v_exp_f32_e32 v100, v100
	v_exp_f32_e32 v101, v101
	v_exp_f32_e32 v102, v102
	v_mfma_f32_16x16x32_bf16 v[116:119], v[68:71], v[12:15], v[20:23]
	v_exp_f32_e32 v103, v103
	v_exp_f32_e32 v104, v104
	v_exp_f32_e32 v105, v105
	v_exp_f32_e32 v106, v106
	v_exp_f32_e32 v107, v107
	v_exp_f32_e32 v110, v110
	v_exp_f32_e32 v111, v111
	v_mfma_f32_16x16x32_bf16 v[116:119], v[64:67], v[16:19], v[116:119]
	v_exp_f32_e32 v112, v112
	v_exp_f32_e32 v113, v113
	v_cndmask_b32_e64 v100, 0, v100, s[58:59]
	v_cndmask_b32_e64 v101, 0, v101, s[56:57]
	v_cndmask_b32_e64 v102, 0, v102, s[54:55]
	v_cndmask_b32_e64 v103, 0, v103, s[50:51]
	v_cndmask_b32_e64 v104, 0, v104, s[52:53]
	v_cndmask_b32_e64 v105, 0, v105, s[48:49]
	v_cndmask_b32_e64 v106, 0, v106, s[46:47]
	v_cndmask_b32_e64 v107, 0, v107, s[42:43]
	v_cndmask_b32_e64 v110, 0, v110, s[44:45]
	v_cndmask_b32_e64 v111, 0, v111, s[40:41]
	v_cndmask_b32_e64 v112, 0, v112, s[38:39]
	v_cndmask_b32_e32 v113, 0, v113, vcc
	v_exp_f32_e32 v193, v116
	v_exp_f32_e32 v198, v117
	v_mul_f32_e32 v116, v183, v100
	v_fmac_f32_e32 v248, v183, v100
	v_mul_f32_e32 v100, v183, v101
	v_fmac_f32_e32 v249, v183, v101
	v_mul_f32_e32 v101, v183, v102
	v_fmac_f32_e32 v250, v183, v102
	v_mul_f32_e32 v102, v183, v103
	v_fmac_f32_e32 v247, v183, v103
	v_mul_f32_e32 v103, v183, v104
	v_fmac_f32_e32 v244, v183, v104
	v_mul_f32_e32 v104, v183, v105
	v_fmac_f32_e32 v245, v183, v105
	v_mul_f32_e32 v105, v183, v106
	v_fmac_f32_e32 v246, v183, v106
	v_mul_f32_e32 v106, v183, v107
	v_fmac_f32_e32 v240, v183, v107
	v_mul_f32_e32 v107, v183, v110
	v_mul_f32_e32 v117, v183, v111
	v_exp_f32_e32 v199, v118
	v_exp_f32_e32 v251, v119
	v_mul_f32_e32 v118, v183, v112
	v_fmac_f32_e32 v242, v183, v112
	v_mul_f32_e32 v119, v183, v113
	v_fmac_f32_e32 v243, v183, v113
	v_cvt_pk_bf16_f32 v112, v103, v104
	v_cvt_pk_bf16_f32 v113, v105, v106
	v_cvt_pk_bf16_f32 v128, v107, v117
	ds_read_b64 v[104:105], v239 offset:1024
	ds_read_b64 v[106:107], v239 offset:1056
	ds_read_b64 v[120:121], v238 offset:1280
	ds_read_b64 v[122:123], v238 offset:1312
	ds_read_b64 v[132:133], v237 offset:1536
	ds_read_b64 v[134:135], v237 offset:1568
	ds_read_b64 v[140:141], v236 offset:1792
	ds_read_b64 v[142:143], v236 offset:1824
	v_fmac_f32_e32 v131, v183, v110
	v_fmac_f32_e32 v241, v183, v111
	v_cvt_pk_bf16_f32 v110, v116, v100
	v_cvt_pk_bf16_f32 v111, v101, v102
	v_cvt_pk_bf16_f32 v129, v118, v119
	s_waitcnt lgkmcnt(6)
	v_mfma_f32_16x16x32_bf16 v[100:103], v[104:107], v[96:99], v[60:63]
	v_mfma_f32_16x16x32_bf16 v[104:107], v[104:107], v[110:113], v[56:59]
	s_waitcnt lgkmcnt(4)
	v_mfma_f32_16x16x32_bf16 v[116:119], v[120:123], v[96:99], v[52:55]
	v_mfma_f32_16x16x32_bf16 v[120:123], v[120:123], v[110:113], v[48:51]
	s_waitcnt lgkmcnt(2)
	v_mfma_f32_16x16x32_bf16 v[124:127], v[132:135], v[96:99], v[44:47]
	v_mfma_f32_16x16x32_bf16 v[132:135], v[132:135], v[110:113], v[40:43]
	s_waitcnt lgkmcnt(0)
	v_mfma_f32_16x16x32_bf16 v[136:139], v[140:143], v[96:99], v[36:39]
	ds_read_b64 v[96:97], v239 offset:1088
	ds_read_b64 v[98:99], v239 offset:1120
	ds_read_b64 v[152:153], v238 offset:1344
	ds_read_b64 v[154:155], v238 offset:1376
	ds_read_b64 v[148:149], v237 offset:1600
	ds_read_b64 v[150:151], v237 offset:1632
	ds_read_b64 v[144:145], v236 offset:1856
	ds_read_b64 v[146:147], v236 offset:1888
	v_mfma_f32_16x16x32_bf16 v[140:143], v[140:143], v[110:113], v[32:35]
	v_add_f32_e32 v110, v248, v249
	v_add_f32_e32 v111, v250, v247
	v_add_f32_e32 v110, v110, v111
	ds_bpermute_b32 v111, v233, v247
	ds_bpermute_b32 v112, v233, v234
	v_add_f32_e32 v113, v246, v240
	s_waitcnt lgkmcnt(0)
	v_cndmask_b32_e64 v112, v111, v112, s[36:37]
	v_add_f32_e32 v110, v110, v112
	v_add_f32_e32 v112, v244, v245
	v_add_f32_e32 v112, v112, v113
	ds_bpermute_b32 v113, v233, v240
	s_waitcnt lgkmcnt(0)
	v_cndmask_b32_e64 v111, v113, v111, s[36:37]
	v_add_f32_e32 v111, v112, v111
	ds_write2_b32 v235, v110, v111 offset1:4
	v_add_f32_e32 v111, v242, v243
	ds_bpermute_b32 v242, v233, v243
	v_add_f32_e32 v110, v131, v241
	v_add_f32_e32 v110, v110, v111
	s_waitcnt lgkmcnt(0)
	v_cndmask_b32_e64 v111, v242, v113, s[36:37]
	v_add_f32_e32 v110, v110, v111
	ds_write_b32 v235, v110 offset:32
	v_add_u32_e32 v110, 50, v2
	v_add_u32_e32 v111, 48, v2
	v_cmp_lt_u32_e64 s[38:39], v110, v171
	v_add_u32_e32 v110, 49, v2
	v_add_u32_e32 v2, 51, v2
	v_cmp_lt_u32_e32 vcc, v111, v174
	v_cmp_lt_u32_e64 s[40:41], v2, v171
	v_cmp_lt_u32_e64 s[42:43], v110, v174
	v_cndmask_b32_e64 v111, 0, v130, s[38:39]
	v_cndmask_b32_e32 v110, 0, v115, vcc
	v_cndmask_b32_e64 v2, 0, v114, s[42:43]
	v_cndmask_b32_e64 v3, 0, v3, s[40:41]
	v_pk_mul_f32 v[112:113], v[184:185], v[110:111]
	v_pk_fma_f32 v[114:115], v[184:185], v[110:111], 0 op_sel_hi:[1,1,0]
	v_pk_mul_f32 v[110:111], v[184:185], v[2:3]
	v_cndmask_b32_e64 v130, 0, v198, s[42:43]
	v_cvt_pk_bf16_f32 v110, v112, v110
	v_cvt_pk_bf16_f32 v111, v113, v111
	v_cndmask_b32_e64 v113, 0, v199, s[38:39]
	v_cndmask_b32_e32 v112, 0, v193, vcc
	v_cndmask_b32_e64 v131, 0, v251, s[40:41]
	v_pk_fma_f32 v[2:3], v[184:185], v[2:3], 0 op_sel_hi:[1,1,0]
	v_pk_mul_f32 v[198:199], v[186:187], v[112:113]
	v_pk_fma_f32 v[240:241], v[186:187], v[112:113], v[114:115]
	v_pk_mul_f32 v[112:113], v[186:187], v[130:131]
	v_pk_fma_f32 v[2:3], v[186:187], v[130:131], v[2:3]
	v_cvt_pk_bf16_f32 v130, v198, v112
	v_cvt_pk_bf16_f32 v131, v199, v113
	v_mfma_f32_16x16x32_bf16 v[112:115], v[96:99], v[108:111], v[100:103]
	s_nop 0
	v_mfma_f32_16x16x32_bf16 v[96:99], v[96:99], v[128:131], v[104:107]
	v_mfma_f32_16x16x32_bf16 v[116:119], v[152:155], v[108:111], v[116:119]
	v_mfma_f32_16x16x32_bf16 v[100:103], v[152:155], v[128:131], v[120:123]
	v_mfma_f32_16x16x32_bf16 v[120:123], v[148:151], v[108:111], v[124:127]
	v_mfma_f32_16x16x32_bf16 v[104:107], v[148:151], v[128:131], v[132:135]
	v_mfma_f32_16x16x32_bf16 v[124:127], v[144:147], v[108:111], v[136:139]
	v_mfma_f32_16x16x32_bf16 v[108:111], v[144:147], v[128:131], v[140:143]
	v_add_f32_e64 v128, v240, v2
	v_add_f32_e64 v129, v241, v3
	v_add_f32_e32 v2, v128, v129
	ds_bpermute_b32 v128, v233, v3
	s_waitcnt lgkmcnt(0)
	v_cndmask_b32_e64 v128, v128, v242, s[36:37]
	s_cbranch_execnz .LBB0_229
	.p2align	6

.LBB0_260:
	s_lshl_b32 s15, s7, 1
	s_bitcmp1_b32 s7, 0
	s_cselect_b32 s0, 0x9000, 0
	s_add_i32 s18, s0, 0
	s_andn2_b32 s0, 1, s7
	s_mul_i32 s0, s0, 0x9000
	v_mov_b64_e32 v[32:33], v[76:77]
	v_mov_b64_e32 v[36:37], v[80:81]
	v_mov_b64_e32 v[40:41], v[72:73]
	v_mov_b64_e32 v[44:45], v[92:93]
	v_mov_b64_e32 v[48:49], v[68:69]
	v_mov_b64_e32 v[52:53], v[88:89]
	v_mov_b64_e32 v[56:57], v[64:65]
	v_mov_b64_e32 v[60:61], v[84:85]
	v_add_u32_e32 v0, s0, v129
	s_mov_b64 s[8:9], -1
	v_mov_b64_e32 v[34:35], v[78:79]
	v_mov_b64_e32 v[38:39], v[82:83]
	v_mov_b64_e32 v[42:43], v[74:75]
	v_mov_b64_e32 v[46:47], v[94:95]
	v_mov_b64_e32 v[50:51], v[70:71]
	v_mov_b64_e32 v[54:55], v[90:91]
	v_mov_b64_e32 v[58:59], v[66:67]
	v_mov_b64_e32 v[62:63], v[86:87]
	s_mov_b32 s19, 0
	s_branch .LBB0_262
	.p2align	6

.LBB0_266:
	s_add_i32 s19, s18, s0
	v_add3_u32 v64, s19, v138, v139
	s_waitcnt lgkmcnt(7)
	ds_read_b128 v[124:127], v64
	s_waitcnt lgkmcnt(7)
	ds_read_b128 v[120:123], v64 offset:64
	s_waitcnt lgkmcnt(7)
	ds_read_b128 v[116:119], v64 offset:2304
	s_waitcnt lgkmcnt(7)
	ds_read_b128 v[96:99], v64 offset:2368
	s_waitcnt lgkmcnt(7)
	ds_read_b128 v[100:103], v64 offset:4608
	s_waitcnt lgkmcnt(7)
	ds_read_b128 v[104:107], v64 offset:4672
	s_waitcnt lgkmcnt(7)
	ds_read_b128 v[108:111], v64 offset:6912
	s_waitcnt lgkmcnt(7)
	ds_read_b128 v[112:115], v64 offset:6976
	s_lshl_b32 s26, s26, 6
	s_add_i32 s26, s26, s2
	v_sub_u32_e32 v64, s26, v3
	v_cmp_lt_u32_e32 vcc, s96, v64
	s_cbranch_vccz .LBB0_271
	s_waitcnt lgkmcnt(7)
	v_mfma_f32_16x16x32_bf16 v[64:67], v[124:127], v[4:7], v[20:23]
	v_add_u32_e32 v76, s26, v140
	v_add_u32_e32 v80, 1, v76
	v_cmp_gt_u32_e64 s[58:59], s22, v76
	s_waitcnt lgkmcnt(6)
	v_mfma_f32_16x16x32_bf16 v[64:67], v[120:123], v[8:11], v[64:67]
	v_cmp_gt_u32_e64 s[56:57], s22, v80
	v_add_u32_e32 v81, 2, v76
	v_add_u32_e32 v82, 3, v76
	s_waitcnt lgkmcnt(5)
	v_mfma_f32_16x16x32_bf16 v[68:71], v[116:119], v[4:7], v[20:23]
	v_cmp_gt_u32_e64 s[60:61], s22, v81
	s_nop 1
	v_exp_f32_e32 v64, v64
	v_exp_f32_e32 v65, v65
	s_waitcnt lgkmcnt(4)
	v_mfma_f32_16x16x32_bf16 v[68:71], v[96:99], v[8:11], v[68:71]
	v_cmp_gt_u32_e64 s[62:63], s22, v82
	v_cndmask_b32_e64 v95, 0, v64, s[58:59]
	v_cndmask_b32_e64 v80, 0, v65, s[56:57]
	v_exp_f32_e32 v64, v66
	v_exp_f32_e32 v65, v67
	s_waitcnt lgkmcnt(3)
	v_mfma_f32_16x16x32_bf16 v[72:75], v[100:103], v[4:7], v[20:23]
	v_add_u32_e32 v83, 16, v76
	v_cndmask_b32_e64 v81, 0, v64, s[60:61]
	v_exp_f32_e32 v64, v68
	v_cndmask_b32_e64 v82, 0, v65, s[62:63]
	v_exp_f32_e32 v65, v69
	v_add_u32_e32 v84, 17, v76
	v_cmp_gt_u32_e64 s[64:65], s22, v83
	v_cmp_gt_u32_e64 s[48:49], s22, v84
	s_waitcnt lgkmcnt(2)
	v_mfma_f32_16x16x32_bf16 v[72:75], v[104:107], v[8:11], v[72:75]
	v_cndmask_b32_e64 v83, 0, v64, s[64:65]
	v_exp_f32_e32 v64, v70
	v_cndmask_b32_e64 v84, 0, v65, s[48:49]
	v_exp_f32_e32 v65, v71
	v_add_u32_e32 v85, 18, v76
	v_add_u32_e32 v86, 19, v76
	v_cmp_gt_u32_e64 s[50:51], s22, v85
	v_cmp_gt_u32_e64 s[52:53], s22, v86
	v_add_u32_e32 v87, 32, v76
	v_add_u32_e32 v88, 33, v76
	v_add_u32_e32 v89, 34, v76
	v_add_u32_e32 v90, 35, v76
	v_add_u32_e32 v91, 48, v76
	v_add_u32_e32 v92, 49, v76
	v_add_u32_e32 v93, 50, v76
	v_add_u32_e32 v94, 51, v76
	s_waitcnt lgkmcnt(1)
	v_mfma_f32_16x16x32_bf16 v[76:79], v[108:111], v[4:7], v[20:23]
	v_cndmask_b32_e64 v85, 0, v64, s[50:51]
	v_exp_f32_e32 v64, v72
	v_cndmask_b32_e64 v86, 0, v65, s[52:53]
	v_exp_f32_e32 v65, v73
	v_cmp_gt_u32_e64 s[54:55], s22, v87
	v_cmp_gt_u32_e64 s[40:41], s22, v88
	s_waitcnt lgkmcnt(0)
	v_mfma_f32_16x16x32_bf16 v[76:79], v[112:115], v[8:11], v[76:79]
	v_cndmask_b32_e64 v87, 0, v64, s[54:55]
	v_exp_f32_e32 v64, v74
	v_cndmask_b32_e64 v88, 0, v65, s[40:41]
	v_exp_f32_e32 v65, v75
	v_cmp_gt_u32_e32 vcc, s22, v89
	v_cmp_gt_u32_e64 s[38:39], s22, v90
	v_cmp_gt_u32_e64 s[46:47], s22, v91
	v_cndmask_b32_e32 v89, 0, v64, vcc
	v_exp_f32_e32 v64, v76
	v_cndmask_b32_e64 v90, 0, v65, s[38:39]
	v_exp_f32_e32 v65, v77
	v_cmp_gt_u32_e64 s[36:37], s22, v92
	v_cndmask_b32_e64 v91, 0, v64, s[46:47]
	v_exp_f32_e32 v64, v78
	v_cndmask_b32_e64 v92, 0, v65, s[36:37]
	v_exp_f32_e32 v65, v79
	v_cmp_gt_u32_e64 s[42:43], s22, v93
	v_cmp_gt_u32_e64 s[44:45], s22, v94
	v_add_f32_e32 v69, v83, v84
	v_cndmask_b32_e64 v93, 0, v64, s[42:43]
	v_cndmask_b32_e64 v94, 0, v65, s[44:45]
	v_add_f32_e32 v64, v95, v80
	v_add_f32_e32 v65, v81, v82
	v_add_f32_e32 v70, v85, v86
	v_add_f32_e32 v68, v64, v65
	v_mfma_f32_16x16x32_bf16 v[64:67], v[124:127], v[12:15], v[20:23]
	v_add_f32_e32 v69, v69, v70
	v_add_f32_e32 v72, v68, v69
	v_add_f32_e32 v68, v87, v88
	v_add_f32_e32 v69, v89, v90
	v_add_f32_e32 v74, v91, v92
	v_add_f32_e32 v75, v93, v94
	v_add_f32_e32 v73, v68, v69
	v_add_f32_e32 v74, v74, v75
	v_add_f32_e32 v73, v73, v74
	v_mfma_f32_16x16x32_bf16 v[64:67], v[120:123], v[16:19], v[64:67]
	v_add_f32_e32 v72, v72, v73
	v_add_f32_e32 v136, v134, v72
	v_add3_u32 v152, s19, v141, v139
	v_mfma_f32_16x16x32_bf16 v[68:71], v[116:119], v[12:15], v[20:23]
	v_add_u32_e32 v185, 0x2800, v152
	s_nop 2
	v_exp_f32_e32 v64, v64
	v_cvt_pk_bf16_f32 v76, v95, v80
	v_mfma_f32_16x16x32_bf16 v[72:75], v[100:103], v[12:15], v[20:23]
	v_cvt_pk_bf16_f32 v77, v81, v82
	v_cvt_pk_bf16_f32 v80, v87, v88
	v_cvt_pk_bf16_f32 v81, v89, v90
	v_mfma_f32_16x16x32_bf16 v[68:71], v[96:99], v[16:19], v[68:71]
	v_cvt_pk_bf16_f32 v82, v91, v92
	ds_read_b64 v[88:89], v185 offset:1280
	ds_read_b64 v[90:91], v185 offset:1312
	v_cndmask_b32_e64 v137, 0, v64, s[58:59]
	v_mfma_f32_16x16x32_bf16 v[72:75], v[104:107], v[16:19], v[72:75]
	v_exp_f32_e32 v64, v65
	v_exp_f32_e32 v65, v66
	v_exp_f32_e32 v66, v67
	s_nop 0
	v_exp_f32_e32 v67, v68
	v_exp_f32_e32 v68, v69
	v_exp_f32_e32 v69, v70
	v_exp_f32_e32 v70, v71
	v_exp_f32_e32 v71, v72
	v_exp_f32_e32 v72, v73
	v_cvt_pk_bf16_f32 v78, v83, v84
	v_cvt_pk_bf16_f32 v79, v85, v86
	v_mfma_f32_16x16x32_bf16 v[84:87], v[108:111], v[12:15], v[20:23]
	v_cndmask_b32_e64 v143, 0, v64, s[56:57]
	v_cndmask_b32_e64 v171, 0, v65, s[60:61]
	v_cndmask_b32_e64 v172, 0, v66, s[62:63]
	v_cndmask_b32_e64 v173, 0, v67, s[64:65]
	v_cndmask_b32_e64 v193, 0, v68, s[48:49]
	v_cndmask_b32_e64 v198, 0, v69, s[50:51]
	v_cndmask_b32_e64 v199, 0, v70, s[52:53]
	v_add_u32_e32 v174, 0x2000, v152
	v_cndmask_b32_e64 v225, 0, v71, s[54:55]
	v_cvt_pk_bf16_f32 v68, v137, v143
	v_cvt_pk_bf16_f32 v69, v171, v172
	v_cvt_pk_bf16_f32 v70, v173, v193
	v_cvt_pk_bf16_f32 v71, v198, v199
	v_add_u32_e32 v226, 0x3000, v152
	v_add_u32_e32 v228, 0x3800, v152
	ds_read_b64 v[64:65], v174 offset:1024
	ds_read_b64 v[66:67], v174 offset:1056
	ds_read_b64 v[144:145], v226 offset:1536
	ds_read_b64 v[146:147], v226 offset:1568
	s_waitcnt lgkmcnt(4)
	v_mfma_f32_16x16x32_bf16 v[148:151], v[88:91], v[76:79], v[52:55]
	v_cndmask_b32_e64 v227, 0, v72, s[40:41]
	v_exp_f32_e32 v176, v74
	v_exp_f32_e32 v177, v75
	v_mfma_f32_16x16x32_bf16 v[72:75], v[88:91], v[68:71], v[48:51]
	ds_read_b64 v[88:89], v228 offset:1792
	ds_read_b64 v[90:91], v228 offset:1824
	v_cndmask_b32_e32 v229, 0, v176, vcc
	v_cndmask_b32_e64 v230, 0, v177, s[38:39]
	v_mfma_f32_16x16x32_bf16 v[84:87], v[112:115], v[16:19], v[84:87]
	ds_read_b64 v[176:177], v174 offset:1088
	ds_read_b64 v[178:179], v174 offset:1120
	v_cvt_pk_bf16_f32 v83, v93, v94
	v_cvt_pk_bf16_f32 v184, v225, v227
	s_waitcnt lgkmcnt(6)
	v_mfma_f32_16x16x32_bf16 v[92:95], v[64:67], v[76:79], v[60:63]
	s_nop 2
	v_exp_f32_e32 v84, v84
	v_mfma_f32_16x16x32_bf16 v[64:67], v[64:67], v[68:71], v[56:59]
	v_cndmask_b32_e64 v231, 0, v84, s[46:47]
	v_exp_f32_e32 v84, v85
	s_waitcnt lgkmcnt(4)
	v_mfma_f32_16x16x32_bf16 v[152:155], v[144:147], v[76:79], v[44:47]
	v_exp_f32_e32 v85, v86
	v_exp_f32_e32 v86, v87
	v_cndmask_b32_e64 v174, 0, v84, s[36:37]
	v_mfma_f32_16x16x32_bf16 v[144:147], v[144:147], v[68:71], v[40:43]
	v_cndmask_b32_e64 v232, 0, v85, s[42:43]
	v_cndmask_b32_e64 v233, 0, v86, s[44:45]
	v_cvt_pk_bf16_f32 v186, v231, v174
	s_waitcnt lgkmcnt(2)
	v_mfma_f32_16x16x32_bf16 v[180:183], v[88:91], v[68:71], v[32:35]
	ds_read_b64 v[68:69], v185 offset:1344
	ds_read_b64 v[70:71], v185 offset:1376
	v_cvt_pk_bf16_f32 v185, v229, v230
	v_cvt_pk_bf16_f32 v187, v232, v233
	s_waitcnt lgkmcnt(2)
	v_mfma_f32_16x16x32_bf16 v[84:87], v[176:179], v[80:83], v[92:95]
	v_mfma_f32_16x16x32_bf16 v[64:67], v[176:179], v[184:187], v[64:67]
	ds_read_b64 v[176:177], v226 offset:1600
	ds_read_b64 v[178:179], v226 offset:1632
	s_nop 0
	v_add_f32_e32 v92, v137, v143
	v_add_f32_e32 v93, v171, v172
	v_mfma_f32_16x16x32_bf16 v[76:79], v[88:91], v[76:79], v[36:39]
	v_add_f32_e32 v92, v92, v93
	v_add_f32_e32 v93, v173, v193
	v_add_f32_e32 v94, v198, v199
	s_waitcnt lgkmcnt(2)
	v_mfma_f32_16x16x32_bf16 v[88:91], v[68:71], v[80:83], v[148:151]
	s_nop 2
	ds_read_b64 v[148:149], v228 offset:1856
	ds_read_b64 v[150:151], v228 offset:1888
	v_mfma_f32_16x16x32_bf16 v[68:71], v[68:71], v[184:187], v[72:75]
	s_nop 2
	v_add_f32_e32 v72, v93, v94
	v_add_f32_e32 v137, v92, v72
	v_add_f32_e32 v72, v225, v227
	v_add_f32_e32 v73, v229, v230
	v_add_f32_e32 v143, v72, v73
	s_waitcnt lgkmcnt(2)
	v_mfma_f32_16x16x32_bf16 v[72:75], v[176:179], v[184:187], v[144:147]
	s_nop 2
	v_add_f32_e32 v144, v231, v174
	v_add_f32_e32 v145, v232, v233
	v_add_f32_e32 v144, v144, v145
	v_mfma_f32_16x16x32_bf16 v[92:95], v[176:179], v[80:83], v[152:155]
	s_waitcnt lgkmcnt(0)
	v_mfma_f32_16x16x32_bf16 v[80:83], v[148:151], v[80:83], v[76:79]
	s_nop 2
	v_add_f32_e32 v76, v143, v144
	v_add_f32_e32 v76, v137, v76
	v_add_f32_e32 v137, v135, v76
	v_mfma_f32_16x16x32_bf16 v[76:79], v[148:151], v[184:187], v[180:183]
	s_cbranch_execnz .LBB0_269
	.p2align	6

.LBB0_622:
	s_lshl_b32 s9, s9, 5
	s_and_b32 s16, s9, 0x60
	s_add_i32 m0, s41, 0x18000
	v_lshl_add_u64 v[8:9], v[8:9], 0, s[20:21]
	s_lshl_b32 s15, s8, 13
	s_lshl_b32 s9, s16, 7
	s_waitcnt vmcnt(2)
	s_barrier
	global_load_lds_dwordx4 v[8:9], off
	v_lshl_add_u64 v[6:7], v[6:7], 0, s[20:21]
	s_add_i32 m0, s41, 0x1a000
	s_add_i32 s45, s41, 0x8000
	s_add_i32 s46, s41, 0xa000
	global_load_lds_dwordx4 v[6:7], off
	v_lshl_add_u64 v[4:5], v[4:5], 0, s[20:21]
	s_mov_b32 m0, s45
	s_add_u32 s12, s36, 0x40080
	global_load_lds_dwordx4 v[4:5], off
	v_lshl_add_u64 v[2:3], v[2:3], 0, s[20:21]
	s_mov_b32 m0, s46
	s_addc_u32 s13, s37, 0
	global_load_lds_dwordx4 v[2:3], off
	s_add_i32 m0, s41, 0x1c000
	v_lshl_add_u64 v[2:3], s[12:13], 0, v[0:1]
	global_load_lds_dwordx4 v[2:3], off
	v_lshl_add_u64 v[2:3], s[12:13], 0, v[134:135]
	s_add_i32 m0, s41, 0x1e000
	s_sext_i32_i8 s27, s0
	global_load_lds_dwordx4 v[2:3], off
	v_lshrrev_b32_e32 v3, 1, v162
	v_and_b32_e32 v3, 24, v3
	s_lshl_b32 s0, s8, 8
	v_and_b32_e32 v2, 15, v162
	v_lshlrev_b32_e32 v4, 1, v3
	s_add_i32 s0, s0, 0
	v_lshl_or_b32 v140, s8, 6, v2
	v_lshl_or_b32 v4, v2, 6, v4
	v_lshlrev_b32_e32 v2, 2, v2
	s_add_i32 s0, s0, 0x20000
	v_and_b32_e32 v5, 32, v2
	v_add_u32_e32 v142, s0, v2
	v_lshlrev_b32_e32 v2, 14, v10
	v_and_b32_e32 v2, 0xffff8000, v2
	v_or_b32_e32 v143, s16, v3
	v_lshl_add_u32 v2, v11, 11, v2
	v_and_b32_e32 v3, 1, v10
	v_lshl_or_b32 v2, v3, 6, v2
	v_lshl_add_u32 v136, v12, 1, v2
	v_lshlrev_b32_e32 v2, 14, v13
	v_and_b32_e32 v2, 0xffff8000, v2
	s_waitcnt vmcnt(6)
	v_lshl_add_u32 v2, v14, 11, v2
	v_and_b32_e32 v3, 1, v13
	v_bitop3_b32 v6, v4, s15, v5 bitop3:0xde
	s_cmpk_lt_u32 s14, 0x100
	v_lshl_or_b32 v2, v3, 6, v2
	v_bitop3_b32 v141, s9, v4, v5 bitop3:0xf6
	s_cselect_b64 s[8:9], -1, 0
	v_mov_b32_e32 v137, v1
	v_lshl_add_u32 v138, v15, 1, v2
	v_mov_b32_e32 v139, v1
	s_mov_b32 s47, 0
	v_add_u32_e32 v144, 0, v6
	s_barrier
	s_branch .LBB0_625
	.p2align	6
.LBB0_623:
	s_mov_b64 s[26:27], 0
	.p2align	6

.LBB0_806:
	s_lshl_b32 s14, s14, 5
	s_and_b32 s17, s14, 0x60
	s_add_i32 m0, s42, 0x18000
	v_lshl_add_u64 v[8:9], v[8:9], 0, s[20:21]
	s_ashr_i32 s31, s13, 3
	s_lshl_b32 s13, s12, 13
	s_lshl_b32 s18, s17, 7
	s_waitcnt vmcnt(2)
	s_barrier
	global_load_lds_dwordx4 v[8:9], off
	v_lshl_add_u64 v[6:7], v[6:7], 0, s[20:21]
	s_add_i32 m0, s42, 0x1a000
	s_add_i32 s46, s42, 0x8000
	s_add_i32 s47, s42, 0xa000
	global_load_lds_dwordx4 v[6:7], off
	v_lshl_add_u64 v[4:5], v[4:5], 0, s[20:21]
	s_mov_b32 m0, s46
	s_add_u32 s14, s38, 0x40080
	global_load_lds_dwordx4 v[4:5], off
	v_lshl_add_u64 v[2:3], v[2:3], 0, s[20:21]
	s_mov_b32 m0, s47
	s_addc_u32 s15, s39, 0
	global_load_lds_dwordx4 v[2:3], off
	s_add_i32 m0, s42, 0x1c000
	v_lshl_add_u64 v[2:3], s[14:15], 0, v[0:1]
	global_load_lds_dwordx4 v[2:3], off
	v_lshl_add_u64 v[2:3], s[14:15], 0, v[134:135]
	s_add_i32 m0, s42, 0x1e000
	v_mov_b32_e32 v137, v1
	global_load_lds_dwordx4 v[2:3], off
	v_and_b32_e32 v2, 15, v162
	v_lshrrev_b32_e32 v3, 1, v162
	v_lshl_or_b32 v144, s12, 6, v2
	v_and_b32_e32 v3, 24, v3
	s_lshl_b32 s12, s12, 8
	v_lshlrev_b32_e32 v4, 1, v3
	s_add_i32 s12, s12, 0
	v_lshl_or_b32 v4, v2, 6, v4
	v_lshlrev_b32_e32 v2, 2, v2
	s_add_i32 s12, s12, 0x20000
	v_and_b32_e32 v5, 32, v2
	v_add_u32_e32 v146, s12, v2
	v_lshlrev_b32_e32 v2, 14, v10
	v_and_b32_e32 v2, 0xffff8000, v2
	v_or_b32_e32 v147, s17, v3
	v_lshl_add_u32 v2, v11, 11, v2
	v_and_b32_e32 v3, 1, v10
	v_lshl_or_b32 v2, v3, 6, v2
	v_lshl_add_u32 v136, v12, 1, v2
	v_lshlrev_b32_e32 v2, 14, v13
	v_and_b32_e32 v2, 0xffff8000, v2
	s_waitcnt vmcnt(6)
	v_lshl_add_u32 v2, v14, 11, v2
	v_and_b32_e32 v3, 1, v13
	v_bitop3_b32 v6, v4, s13, v5 bitop3:0xde
	s_cmpk_lt_u32 s16, 0x100
	v_lshl_or_b32 v2, v3, 6, v2
	v_bitop3_b32 v145, s18, v4, v5 bitop3:0xf6
	s_cselect_b64 s[12:13], -1, 0
	v_lshl_add_u32 v138, v15, 1, v2
	v_mov_b32_e32 v139, v1
	s_mov_b32 s49, 0
	v_add_u32_e32 v148, 0, v6
	s_barrier
	s_branch .LBB0_809
	.p2align	6
.LBB0_807:
	s_mov_b64 s[30:31], 0
	.p2align	6
